# accumulator zeroing with v_mov_b64 (64 instead of 128 instr per unit) in all 4 GEMMs
# speedup vs baseline: 1.2058x; 1.0029x over previous
.LBB0_60:
	s_ashr_i32 s21, s20, 31
	s_lshl_b64 s[4:5], s[20:21], 19
	s_add_u32 s24, s66, s4
	s_addc_u32 s25, s67, s5
	s_and_b64 s[4:5], s[22:23], exec
	s_cselect_b32 s21, s25, s1
	s_cselect_b32 s27, s24, s0
	s_lshl_b32 s29, s52, 8
	s_or_b32 s30, s29, 0x80
	s_add_u32 s31, s0, 0x100
	v_mov_b64_e32 v[0:1], 0
	v_mov_b64_e32 v[2:3], 0
	v_mov_b64_e32 v[4:5], 0
	v_mov_b64_e32 v[6:7], 0
	v_mov_b64_e32 v[8:9], 0
	v_mov_b64_e32 v[10:11], 0
	v_mov_b64_e32 v[12:13], 0
	v_mov_b64_e32 v[14:15], 0
	v_mov_b64_e32 v[16:17], 0
	v_mov_b64_e32 v[18:19], 0
	v_mov_b64_e32 v[20:21], 0
	v_mov_b64_e32 v[22:23], 0
	v_mov_b64_e32 v[24:25], 0
	v_mov_b64_e32 v[26:27], 0
	v_mov_b64_e32 v[28:29], 0
	v_mov_b64_e32 v[30:31], 0
	v_mov_b64_e32 v[32:33], 0
	v_mov_b64_e32 v[34:35], 0
	v_mov_b64_e32 v[36:37], 0
	v_mov_b64_e32 v[38:39], 0
	v_mov_b64_e32 v[40:41], 0
	v_mov_b64_e32 v[42:43], 0
	v_mov_b64_e32 v[44:45], 0
	v_mov_b64_e32 v[46:47], 0
	v_mov_b64_e32 v[48:49], 0
	v_mov_b64_e32 v[50:51], 0
	v_mov_b64_e32 v[52:53], 0
	v_mov_b64_e32 v[54:55], 0
	v_mov_b64_e32 v[56:57], 0
	v_mov_b64_e32 v[58:59], 0
	v_mov_b64_e32 v[60:61], 0
	v_mov_b64_e32 v[62:63], 0
	v_mov_b64_e32 v[64:65], 0
	v_mov_b64_e32 v[66:67], 0
	v_mov_b64_e32 v[68:69], 0
	v_mov_b64_e32 v[70:71], 0
	v_mov_b64_e32 v[72:73], 0
	v_mov_b64_e32 v[74:75], 0
	v_mov_b64_e32 v[76:77], 0
	v_mov_b64_e32 v[78:79], 0
	v_mov_b64_e32 v[80:81], 0
	v_mov_b64_e32 v[82:83], 0
	v_mov_b64_e32 v[84:85], 0
	v_mov_b64_e32 v[86:87], 0
	v_mov_b64_e32 v[88:89], 0
	v_mov_b64_e32 v[90:91], 0
	v_mov_b64_e32 v[92:93], 0
	v_mov_b64_e32 v[94:95], 0
	v_mov_b64_e32 v[96:97], 0
	v_mov_b64_e32 v[98:99], 0
	v_mov_b64_e32 v[100:101], 0
	v_mov_b64_e32 v[102:103], 0
	v_mov_b64_e32 v[104:105], 0
	v_mov_b64_e32 v[106:107], 0
	v_mov_b64_e32 v[108:109], 0
	v_mov_b64_e32 v[110:111], 0
	v_mov_b64_e32 v[112:113], 0
	v_mov_b64_e32 v[114:115], 0
	v_mov_b64_e32 v[116:117], 0
	v_mov_b64_e32 v[118:119], 0
	v_mov_b64_e32 v[120:121], 0
	v_mov_b64_e32 v[122:123], 0
	v_mov_b64_e32 v[124:125], 0
	v_mov_b64_e32 v[126:127], 0
	s_addc_u32 s53, s1, 0
	s_mov_b32 s54, -2
	s_mov_b64 s[0:1], 0

.LBB0_720:
	s_ashr_i32 s15, s14, 31
	s_lshl_b64 s[18:19], s[14:15], 19
	s_add_u32 s18, s13, s18
	s_addc_u32 s19, s26, s19
	s_and_b64 s[22:23], s[16:17], exec
	s_cselect_b32 s15, s19, s21
	s_cselect_b32 s46, s18, s20
	s_lshl_b32 s47, s43, 8
	s_or_b32 s48, s47, 0x80
	s_add_u32 s49, s20, 0x100
	v_mov_b64_e32 v[0:1], 0
	v_mov_b64_e32 v[2:3], 0
	v_mov_b64_e32 v[4:5], 0
	v_mov_b64_e32 v[6:7], 0
	v_mov_b64_e32 v[8:9], 0
	v_mov_b64_e32 v[10:11], 0
	v_mov_b64_e32 v[12:13], 0
	v_mov_b64_e32 v[14:15], 0
	v_mov_b64_e32 v[16:17], 0
	v_mov_b64_e32 v[18:19], 0
	v_mov_b64_e32 v[20:21], 0
	v_mov_b64_e32 v[22:23], 0
	v_mov_b64_e32 v[24:25], 0
	v_mov_b64_e32 v[26:27], 0
	v_mov_b64_e32 v[28:29], 0
	v_mov_b64_e32 v[30:31], 0
	v_mov_b64_e32 v[32:33], 0
	v_mov_b64_e32 v[34:35], 0
	v_mov_b64_e32 v[36:37], 0
	v_mov_b64_e32 v[38:39], 0
	v_mov_b64_e32 v[40:41], 0
	v_mov_b64_e32 v[42:43], 0
	v_mov_b64_e32 v[44:45], 0
	v_mov_b64_e32 v[46:47], 0
	v_mov_b64_e32 v[48:49], 0
	v_mov_b64_e32 v[50:51], 0
	v_mov_b64_e32 v[52:53], 0
	v_mov_b64_e32 v[54:55], 0
	v_mov_b64_e32 v[56:57], 0
	v_mov_b64_e32 v[58:59], 0
	v_mov_b64_e32 v[60:61], 0
	v_mov_b64_e32 v[62:63], 0
	v_mov_b64_e32 v[64:65], 0
	v_mov_b64_e32 v[66:67], 0
	v_mov_b64_e32 v[68:69], 0
	v_mov_b64_e32 v[70:71], 0
	v_mov_b64_e32 v[72:73], 0
	v_mov_b64_e32 v[74:75], 0
	v_mov_b64_e32 v[76:77], 0
	v_mov_b64_e32 v[78:79], 0
	v_mov_b64_e32 v[80:81], 0
	v_mov_b64_e32 v[82:83], 0
	v_mov_b64_e32 v[84:85], 0
	v_mov_b64_e32 v[86:87], 0
	v_mov_b64_e32 v[88:89], 0
	v_mov_b64_e32 v[90:91], 0
	v_mov_b64_e32 v[92:93], 0
	v_mov_b64_e32 v[94:95], 0
	v_mov_b64_e32 v[96:97], 0
	v_mov_b64_e32 v[98:99], 0
	v_mov_b64_e32 v[100:101], 0
	v_mov_b64_e32 v[102:103], 0
	v_mov_b64_e32 v[104:105], 0
	v_mov_b64_e32 v[106:107], 0
	v_mov_b64_e32 v[108:109], 0
	v_mov_b64_e32 v[110:111], 0
	v_mov_b64_e32 v[112:113], 0
	v_mov_b64_e32 v[114:115], 0
	v_mov_b64_e32 v[116:117], 0
	v_mov_b64_e32 v[118:119], 0
	v_mov_b64_e32 v[120:121], 0
	v_mov_b64_e32 v[122:123], 0
	v_mov_b64_e32 v[124:125], 0
	v_mov_b64_e32 v[126:127], 0
	s_addc_u32 s50, s21, 0
	s_mov_b32 s51, -2
	s_mov_b64 s[20:21], 0
	s_waitcnt vmcnt(0)

.LBB0_1247:
	s_ashr_i32 s17, s16, 31
	s_lshl_b64 s[20:21], s[16:17], 18
	s_add_u32 s20, s88, s20
	s_addc_u32 s21, s89, s21
	s_and_b64 s[24:25], s[18:19], exec
	s_cselect_b32 s17, s21, s23
	s_cselect_b32 s50, s20, s22
	s_lshl_b32 s51, s46, 8
	s_or_b32 s52, s51, 0x80
	s_add_u32 s53, s22, 0x100
	v_mov_b64_e32 v[32:33], 0
	v_mov_b64_e32 v[34:35], 0
	v_mov_b64_e32 v[36:37], 0
	v_mov_b64_e32 v[38:39], 0
	v_mov_b64_e32 v[40:41], 0
	v_mov_b64_e32 v[42:43], 0
	v_mov_b64_e32 v[44:45], 0
	v_mov_b64_e32 v[46:47], 0
	v_mov_b64_e32 v[48:49], 0
	v_mov_b64_e32 v[50:51], 0
	v_mov_b64_e32 v[52:53], 0
	v_mov_b64_e32 v[54:55], 0
	v_mov_b64_e32 v[56:57], 0
	v_mov_b64_e32 v[58:59], 0
	v_mov_b64_e32 v[60:61], 0
	v_mov_b64_e32 v[62:63], 0
	v_mov_b64_e32 v[64:65], 0
	v_mov_b64_e32 v[66:67], 0
	v_mov_b64_e32 v[68:69], 0
	v_mov_b64_e32 v[70:71], 0
	v_mov_b64_e32 v[72:73], 0
	v_mov_b64_e32 v[74:75], 0
	v_mov_b64_e32 v[76:77], 0
	v_mov_b64_e32 v[78:79], 0
	v_mov_b64_e32 v[80:81], 0
	v_mov_b64_e32 v[82:83], 0
	v_mov_b64_e32 v[84:85], 0
	v_mov_b64_e32 v[86:87], 0
	v_mov_b64_e32 v[88:89], 0
	v_mov_b64_e32 v[90:91], 0
	v_mov_b64_e32 v[92:93], 0
	v_mov_b64_e32 v[94:95], 0
	v_mov_b64_e32 v[96:97], 0
	v_mov_b64_e32 v[98:99], 0
	v_mov_b64_e32 v[100:101], 0
	v_mov_b64_e32 v[102:103], 0
	v_mov_b64_e32 v[104:105], 0
	v_mov_b64_e32 v[106:107], 0
	v_mov_b64_e32 v[108:109], 0
	v_mov_b64_e32 v[110:111], 0
	v_mov_b64_e32 v[112:113], 0
	v_mov_b64_e32 v[114:115], 0
	v_mov_b64_e32 v[116:117], 0
	v_mov_b64_e32 v[118:119], 0
	v_mov_b64_e32 v[120:121], 0
	v_mov_b64_e32 v[122:123], 0
	v_mov_b64_e32 v[124:125], 0
	v_mov_b64_e32 v[126:127], 0
	v_mov_b64_e32 v[128:129], 0
	v_mov_b64_e32 v[130:131], 0
	v_mov_b64_e32 v[132:133], 0
	v_mov_b64_e32 v[134:135], 0
	v_mov_b64_e32 v[136:137], 0
	v_mov_b64_e32 v[138:139], 0
	v_mov_b64_e32 v[140:141], 0
	v_mov_b64_e32 v[142:143], 0
	v_mov_b64_e32 v[144:145], 0
	v_mov_b64_e32 v[146:147], 0
	v_mov_b64_e32 v[148:149], 0
	v_mov_b64_e32 v[150:151], 0
	v_mov_b64_e32 v[152:153], 0
	v_mov_b64_e32 v[154:155], 0
	v_mov_b64_e32 v[156:157], 0
	v_mov_b64_e32 v[158:159], 0
	s_addc_u32 s56, s23, 0
	s_mov_b32 s57, -2
	s_mov_b64 s[22:23], 0

.LBB0_1323:
	s_lshl_b32 s48, s43, 8
	s_or_b32 s49, s48, 0x80
	s_add_u32 s50, s18, 0x100
	v_mov_b64_e32 v[32:33], 0
	v_mov_b64_e32 v[34:35], 0
	v_mov_b64_e32 v[36:37], 0
	v_mov_b64_e32 v[38:39], 0
	v_mov_b64_e32 v[40:41], 0
	v_mov_b64_e32 v[42:43], 0
	v_mov_b64_e32 v[44:45], 0
	v_mov_b64_e32 v[46:47], 0
	v_mov_b64_e32 v[48:49], 0
	v_mov_b64_e32 v[50:51], 0
	v_mov_b64_e32 v[52:53], 0
	v_mov_b64_e32 v[54:55], 0
	v_mov_b64_e32 v[56:57], 0
	v_mov_b64_e32 v[58:59], 0
	v_mov_b64_e32 v[60:61], 0
	v_mov_b64_e32 v[62:63], 0
	v_mov_b64_e32 v[64:65], 0
	v_mov_b64_e32 v[66:67], 0
	v_mov_b64_e32 v[68:69], 0
	v_mov_b64_e32 v[70:71], 0
	v_mov_b64_e32 v[72:73], 0
	v_mov_b64_e32 v[74:75], 0
	v_mov_b64_e32 v[76:77], 0
	v_mov_b64_e32 v[78:79], 0
	v_mov_b64_e32 v[80:81], 0
	v_mov_b64_e32 v[82:83], 0
	v_mov_b64_e32 v[84:85], 0
	v_mov_b64_e32 v[86:87], 0
	v_mov_b64_e32 v[88:89], 0
	v_mov_b64_e32 v[90:91], 0
	v_mov_b64_e32 v[92:93], 0
	v_mov_b64_e32 v[94:95], 0
	v_mov_b64_e32 v[96:97], 0
	v_mov_b64_e32 v[98:99], 0
	v_mov_b64_e32 v[100:101], 0
	v_mov_b64_e32 v[102:103], 0
	v_mov_b64_e32 v[104:105], 0
	v_mov_b64_e32 v[106:107], 0
	v_mov_b64_e32 v[108:109], 0
	v_mov_b64_e32 v[110:111], 0
	v_mov_b64_e32 v[112:113], 0
	v_mov_b64_e32 v[114:115], 0
	v_mov_b64_e32 v[116:117], 0
	v_mov_b64_e32 v[118:119], 0
	v_mov_b64_e32 v[120:121], 0
	v_mov_b64_e32 v[122:123], 0
	v_mov_b64_e32 v[124:125], 0
	v_mov_b64_e32 v[126:127], 0
	v_mov_b64_e32 v[128:129], 0
	v_mov_b64_e32 v[130:131], 0
	v_mov_b64_e32 v[132:133], 0
	v_mov_b64_e32 v[134:135], 0
	v_mov_b64_e32 v[136:137], 0
	v_mov_b64_e32 v[138:139], 0
	v_mov_b64_e32 v[140:141], 0
	v_mov_b64_e32 v[142:143], 0
	v_mov_b64_e32 v[144:145], 0
	v_mov_b64_e32 v[146:147], 0
	v_mov_b64_e32 v[148:149], 0
	v_mov_b64_e32 v[150:151], 0
	v_mov_b64_e32 v[152:153], 0
	v_mov_b64_e32 v[154:155], 0
	v_mov_b64_e32 v[156:157], 0
	v_mov_b64_e32 v[158:159], 0
	s_addc_u32 s51, s19, 0
	s_mov_b32 s52, -2
	s_mov_b64 s[18:19], 0
